# merge epilogue (helper WGs) de-serialised: g/t loads issued before the write-through stores
# speedup vs baseline: 1.0128x; 1.0016x over previous
.LBB0_537:
	s_or_b64 exec, exec, s[0:1]
	s_and_b64 s[0:1], s[36:37], exec
	s_cselect_b32 s28, 16, 0x1000
	s_add_u32 s64, s76, 0x13d00000
	s_addc_u32 s65, s77, 0
	s_bfe_u32 s68, s96, 0x20006
	s_mul_i32 s0, s68, 0x3700
	s_add_i32 s71, s0, 0
	s_and_b32 s0, s96, 0xffffff00
	s_lshr_b32 s74, s96, 8
	s_add_i32 s84, s0, 0
	s_lshl_b32 s11, s74, 5
	s_add_i32 s80, s84, 0x12600
	s_cmpk_lt_u32 s96, 0x540
	v_readlane_b32 s20, v255, 31
	s_cselect_b64 s[40:41], -1, 0
	s_add_i32 s12, s20, -4
	s_lshl_b32 s13, s12, 2
	s_lshl_b32 s22, s12, 10
	s_cmpk_lt_u32 s96, 0x440
	s_cselect_b64 s[42:43], -1, 0
	s_lshl_b32 s66, s20, 10
	s_cmpk_lt_u32 s96, 0x340
	s_cselect_b64 s[46:47], -1, 0
	s_add_i32 s14, s20, 4
	s_lshl_b32 s15, s14, 2
	s_lshl_b32 s23, s14, 10
	s_cmpk_lt_u32 s96, 0x240
	s_cselect_b64 s[48:49], -1, 0
	s_add_i32 s16, s20, 8
	s_lshl_b32 s17, s16, 2
	s_lshl_b32 s24, s16, 10
	s_cmp_eq_u32 s20, 4
	s_cselect_b64 s[50:51], -1, 0
	s_cmp_eq_u32 s20, 2
	s_mov_b32 s0, 0xfc00000
	s_cselect_b32 s38, s0, 0x13d00000
	s_add_u32 s8, s76, s6
	s_addc_u32 s9, s77, 0
	s_mul_i32 s0, s20, 0x2400
	s_add_i32 s1, 0, 0x1a900
	s_add_i32 s81, s1, s0
	s_lshl_b32 s0, s74, 7
	s_add_i32 s83, s0, 0
	s_add_i32 s82, s81, 0x2000
	s_add_i32 s83, s83, 0x14800
	s_add_i32 s84, s84, 0x12400
	s_lshl_b32 s29, s20, 5
	s_add_u32 s6, s64, s6
	s_addc_u32 s7, s65, 0
	s_lshl_b32 s85, s33, 10
	s_add_u32 s18, s76, 0x10000
	v_writelane_b32 v255, s96, 33
	s_addc_u32 s19, s77, 0
	v_lshl_or_b32 v11, s68, 4, v9
	v_writelane_b32 v255, s18, 34
	v_add_u32_e32 v25, 1, v11
	v_lshlrev_b32_e32 v27, 3, v38
	v_writelane_b32 v255, s19, 35
	v_lshlrev_b32_e32 v10, 7, v25
	v_and_b32_e32 v22, 8, v27
	s_add_i32 s0, 0, 0x1cd00
	s_add_i32 s18, 0, 0x1f100
	v_add3_u32 v91, s1, v10, v22
	v_add3_u32 v92, s0, v10, v22
	v_add3_u32 v93, s18, v10, v22
	v_lshlrev_b32_e32 v10, 8, v25
	s_add_i32 s19, 0, 0x23900
	v_add3_u32 v28, s19, v10, v22
	v_lshlrev_b32_e32 v10, 7, v11
	v_add3_u32 v94, s1, v10, v22
	v_add3_u32 v95, s0, v10, v22
	v_add3_u32 v96, s18, v10, v22
	v_lshlrev_b32_e32 v10, 8, v11
	v_add3_u32 v29, s19, v10, v22
	v_add_u32_e32 v10, 1, v89
	s_add_i32 s19, 0, 0x21500
	v_lshl_add_u32 v32, v10, 7, s19
	v_xor_b32_e32 v10, v10, v39
	v_lshlrev_b32_e32 v10, 4, v10
	v_and_b32_e32 v33, 0x70, v10
	v_lshlrev_b32_e32 v10, 7, v89
	v_add_u32_e32 v34, s19, v10
	s_add_i32 s19, 0, 0x12800
	s_cmp_lg_u32 s12, 16
	v_add_u32_e32 v36, s19, v10
	v_or_b32_e32 v10, s13, v38
	s_cselect_b64 vcc, -1, 0
	v_xor_b32_e32 v22, v89, v39
	v_cndmask_b32_e32 v98, 64, v10, vcc
	v_bitop3_b32 v10, v38, v39, s13 bitop3:0x36
	v_lshlrev_b32_e32 v22, 4, v22
	v_and_or_b32 v10, v10, 7, v41
	v_and_b32_e32 v35, 0x70, v22
	v_lshlrev_b32_e32 v22, 4, v10
	v_mov_b32_e32 v10, 0
	v_mov_b32_e32 v23, v10
	s_cmp_lg_u32 s20, 16
	v_lshl_add_u64 v[48:49], s[4:5], 0, v[22:23]
	v_or_b32_e32 v22, s3, v38
	s_cselect_b64 vcc, -1, 0
	v_cndmask_b32_e32 v99, 64, v22, vcc
	v_bitop3_b32 v22, v38, v39, s3 bitop3:0x36
	v_and_or_b32 v22, v22, 7, v41
	v_lshlrev_b32_e32 v22, 4, v22
	s_cmp_lg_u32 s14, 16
	v_lshl_add_u64 v[50:51], s[4:5], 0, v[22:23]
	v_or_b32_e32 v22, s15, v38
	s_cselect_b64 vcc, -1, 0
	v_cndmask_b32_e32 v100, 64, v22, vcc
	v_bitop3_b32 v22, v38, v39, s15 bitop3:0x36
	v_and_or_b32 v22, v22, 7, v41
	v_lshlrev_b32_e32 v22, 4, v22
	s_cmp_lg_u32 s16, 16
	v_lshl_add_u64 v[52:53], s[4:5], 0, v[22:23]
	v_or_b32_e32 v22, s17, v38
	s_cselect_b64 vcc, -1, 0
	v_cndmask_b32_e32 v101, 64, v22, vcc
	v_bitop3_b32 v22, v38, v39, s17 bitop3:0x36
	v_and_or_b32 v22, v22, 7, v41
	v_lshlrev_b32_e32 v22, 4, v22
	v_lshl_add_u64 v[54:55], s[4:5], 0, v[22:23]
	v_xor_b32_e32 v22, v38, v20
	s_movk_i32 s10, 0x3700
	v_or_b32_e32 v22, v22, v41
	v_lshlrev_b32_e32 v41, 5, v9
	v_lshrrev_b32_e32 v45, 7, v42
	v_cmp_gt_u32_e64 s[0:1], 16, v40
	v_or_b32_e32 v103, v27, v41
	v_lshl_add_u32 v104, v40, 2, s71
	v_add_u32_e32 v40, s71, v41
	v_lshrrev_b32_e32 v41, 2, v9
	v_mul_lo_u32 v45, v45, s10
	v_or_b32_e32 v41, v90, v41
	v_add_u32_e32 v67, 0, v45
	v_bfe_u32 v45, v42, 3, 4
	v_mul_u32_u24_e32 v41, 0x48, v41
	v_and_b32_e32 v21, 12, v21
	v_mul_u32_u24_e32 v45, 0x48, v45
	v_or_b32_e32 v24, s11, v90
	v_add_lshl_u32 v105, v21, v41, 1
	v_lshl_or_b32 v21, v89, 6, v8
	v_add_lshl_u32 v8, v45, v8, 1
	v_mov_b32_e32 v45, v10
	v_and_b32_e32 v26, 7, v25
	v_lshl_add_u64 v[60:61], s[6:7], 0, v[44:45]
	v_cmp_eq_u32_e64 s[6:7], 0, v42
	v_lshrrev_b32_e32 v42, 3, v24
	v_and_b32_e32 v62, 8, v42
	v_bitop3_b32 v63, v42, v26, 5 bitop3:0x6c
	v_or_b32_e32 v63, v63, v62
	v_lshlrev_b32_e32 v68, 4, v63
	v_add_u32_e32 v63, 64, v24
	v_bitop3_b32 v45, v42, v25, 7 bitop3:0x78
	v_lshrrev_b32_e32 v64, 3, v63
	v_xor_b32_e32 v69, v42, v20
	v_bitop3_b32 v42, v42, v20, 5 bitop3:0x6c
	v_and_b32_e32 v65, 8, v64
	v_or_b32_e32 v42, v42, v62
	v_bitop3_b32 v62, v64, v20, 5 bitop3:0x6c
	v_or_b32_e32 v62, v62, v65
	v_lshlrev_b32_e32 v108, 4, v69
	v_lshlrev_b32_e32 v69, 4, v62
	v_or_b32_e32 v62, 16, v24
	v_lshlrev_b32_e32 v22, 4, v22
	v_lshlrev_b32_e32 v71, 1, v63
	v_lshrrev_b32_e32 v63, 3, v62
	v_lshl_add_u64 v[56:57], s[4:5], 0, v[22:23]
	v_xor_b32_e32 v22, v88, v20
	v_bitop3_b32 v26, v64, v26, 5 bitop3:0x6c
	v_bitop3_b32 v64, v63, v25, 7 bitop3:0x78
	v_lshlrev_b32_e32 v22, 4, v22
	v_or_b32_e32 v26, v26, v65
	v_lshlrev_b32_e32 v111, 4, v64
	v_and_b32_e32 v64, 8, v63
	v_bitop3_b32 v65, v63, v25, 7 bitop3:0x28
	s_movk_i32 s18, 0x48
	v_lshl_add_u64 v[58:59], s[8:9], 0, v[22:23]
	v_or_b32_e32 v23, s11, v9
	v_or_b32_e32 v65, v65, v64
	v_mul_u32_u24_e32 v30, 0x48, v11
	v_mul_u32_u24_e32 v31, 0x48, v9
	v_lshlrev_b32_e32 v97, 2, v11
	v_or_b32_e32 v22, 16, v90
	v_lshlrev_b32_e32 v72, 4, v65
	v_add_u32_e32 v65, 0x50, v24
	v_mul_lo_u32 v23, v23, s18
	v_mad_u32_u24 v11, v11, s18, 32
	v_lshlrev_b32_e32 v70, 1, v24
	v_add_lshl_u32 v109, v24, v30, 1
	v_add_lshl_u32 v110, v24, v31, 1
	v_lshrrev_b32_e32 v73, 3, v65
	v_xor_b32_e32 v75, v63, v20
	v_bitop3_b32 v63, v63, v20, 7 bitop3:0x6c
	v_add_lshl_u32 v113, v62, v30, 1
	v_add_lshl_u32 v115, v30, v90, 1
	v_add_lshl_u32 v116, v22, v30, 1
	v_add_u32_e32 v30, 0x480, v23
	v_add_lshl_u32 v119, v11, v90, 1
	v_add_lshl_u32 v120, v11, v22, 1
	v_or_b32_e32 v11, 32, v90
	v_lshlrev_b32_e32 v123, 2, v24
	v_or_b32_e32 v24, 1, v90
	v_cmp_eq_u32_e32 vcc, v90, v9
	v_lshlrev_b32_e32 v106, 5, v20
	v_and_b32_e32 v74, 8, v73
	v_bitop3_b32 v25, v73, v25, 7 bitop3:0x28
	v_or_b32_e32 v63, v63, v64
	v_bitop3_b32 v20, v73, v20, 7 bitop3:0x6c
	v_lshlrev_b32_e32 v73, 1, v62
	v_add_lshl_u32 v114, v62, v31, 1
	v_add_lshl_u32 v118, v30, v90, 1
	v_add_lshl_u32 v122, v11, v30, 1
	v_lshlrev_b32_e32 v124, 2, v62
	v_or_b32_e32 v30, 2, v90
	v_cndmask_b32_e64 v62, 0, 1.0, vcc
	v_cmp_eq_u32_e32 vcc, v24, v9
	v_lshlrev_b32_e32 v112, 4, v75
	v_lshlrev_b32_e32 v75, 4, v63
	v_add_lshl_u32 v117, v90, v23, 1
	v_add_lshl_u32 v121, v11, v23, 1
	v_add_lshl_u32 v125, v90, v31, 1
	v_add_lshl_u32 v23, v11, v31, 1
	v_or_b32_e32 v31, 3, v90
	v_cndmask_b32_e64 v63, 0, 1.0, vcc
	v_cmp_eq_u32_e32 vcc, v30, v9
	v_cmp_eq_u32_e64 s[4:5], 0, v9
	v_mad_u32_u24 v37, v9, s18, 16
	v_cmp_lt_u32_e64 s[8:9], v90, v9
	v_cmp_gt_u32_e64 s[10:11], v90, v9
	v_cmp_lt_u32_e64 s[12:13], v24, v9
	v_cmp_lt_u32_e64 s[14:15], v30, v9
	v_cmp_gt_u32_e64 s[16:17], v30, v9
	v_cmp_lt_u32_e64 s[18:19], v31, v9
	v_cmp_gt_u32_e64 s[20:21], v31, v9
	v_cndmask_b32_e64 v64, 0, 1.0, vcc
	v_cmp_eq_u32_e32 vcc, v31, v9
	v_lshlrev_b32_e32 v9, 2, v9
	v_lshl_add_u32 v24, v38, 10, s97
	s_mov_b32 s3, 0xdc00
	v_add3_u32 v126, v24, v9, s3
	v_and_b32_e32 v9, 3, v39
	s_movk_i32 s25, 0x2400
	v_lshlrev_b32_e32 v43, 2, v21
	v_lshlrev_b32_e32 v21, 1, v21
	v_lshl_or_b32 v9, v9, 3, s29
	v_lshlrev_b32_e32 v24, 1, v41
	s_waitcnt lgkmcnt(0)
	s_barrier
	v_lshlrev_b32_e32 v66, 2, v89
	v_or_b32_e32 v25, v25, v74
	v_or_b32_e32 v20, v20, v74
	v_add3_u32 v128, v9, v24, s25
	v_mov_b32_e32 v9, 0x3540
	v_add_u32_e32 v151, v67, v8
	v_add_u32_e32 v8, 0, v21
	s_mov_b32 s39, 0
	v_and_b32_e32 v102, 48, v39
	v_lshlrev_b32_e32 v26, 4, v26
	v_lshlrev_b32_e32 v42, 4, v42
	v_lshlrev_b32_e32 v25, 4, v25
	v_lshlrev_b32_e32 v20, 4, v20
	v_lshlrev_b32_e32 v74, 1, v65
	v_add_lshl_u32 v22, v37, v90, 1
	v_add_lshl_u32 v11, v11, v37, 1
	v_writelane_b32 v255, s97, 32
	v_lshl_or_b32 v129, v38, 4, v9
	s_add_i32 s3, 0, 0x15c00
	s_add_i32 s88, s22, 0
	s_add_i32 s89, s23, 0
	s_add_i32 s90, s24, 0
	v_add_u32_e32 v9, 0, v66
	v_add_u32_e32 v152, 0x12800, v8
	v_mbcnt_lo_u32_b32 v8, -1, 0
	s_mov_b64 s[52:53], s[38:39]
	v_add_u32_e32 v107, s70, v89
	v_lshlrev_b32_e32 v45, 4, v45
	v_cndmask_b32_e64 v65, 0, 1.0, vcc
	v_add_u32_e32 v127, 0x2d00, v103
	v_writelane_b32 v255, s29, 44
	v_or_b32_e32 v130, 0x3500, v102
	v_add_u32_e32 v131, v28, v68
	v_add_u32_e32 v132, v28, v26
	v_add_u32_e32 v133, v29, v42
	v_add_u32_e32 v134, v29, v69
	v_add_u32_e32 v135, s3, v70
	v_add_u32_e32 v136, s3, v71
	s_mov_b32 s86, 0x4038aa3b
	s_add_i32 s67, 0, 0x10000
	v_add_u32_e32 v137, v28, v72
	v_add_u32_e32 v138, v28, v25
	v_add_u32_e32 v139, v29, v75
	v_add_u32_e32 v140, v29, v20
	v_add_u32_e32 v141, s3, v73
	v_add_u32_e32 v142, s3, v74
	v_add_u32_e32 v143, v32, v33
	v_add_u32_e32 v145, v34, v35
	s_mov_b32 s87, 0xbfb8aa3b
	v_add_u32_e32 v146, v36, v44
	s_add_i32 s88, s88, 0x23900
	s_add_i32 s89, s89, 0x23900
	s_add_i32 s90, s90, 0x23900
	s_add_i32 s91, 0, 0x27900
	s_add_i32 s92, s81, 0x400
	s_add_i32 s93, s81, 0x800
	s_add_i32 s94, s81, 0xc00
	s_add_i32 s95, s81, 0x1400
	s_add_i32 s96, s81, 0x1800
	s_add_i32 s97, s81, 0x1c00
	s_add_i32 s3, 0, 0x16100
	s_add_i32 s69, 0, 0x18500
	v_mov_b32_e32 v147, 0xbf92477c
	v_add_u32_e32 v148, v40, v27
	s_xor_b64 s[54:55], s[26:27], -1
	v_add_u32_e32 v149, 0, v43
	v_add_u32_e32 v150, 0x12400, v9
	v_mov_b32_e32 v153, 0x3a27c5ac
	v_mbcnt_hi_u32_b32 v144, -1, v8
	v_add_u32_e32 v154, s71, v22
	v_add_u32_e32 v155, s71, v23
	v_add_u32_e32 v156, s71, v11
	s_mov_b32 s33, s28
	s_mov_b32 s29, 0
	v_add_u32_e32 v219, v93, v111
	v_add_u32_e32 v238, s69, v122
	v_add_u32_e32 v210, v96, v108
	v_add_u32_e32 v237, s3, v122
	v_add_u32_e32 v225, 0x15d80, v44
	v_add_u32_e32 v220, v91, v111
	v_and_b32_e32 v241, 64, v144
	v_or_b32_e32 v240, v102, v241
	v_add_u32_e32 v216, v94, v112
	v_add_u32_e32 v233, s67, v119
	v_xor_b32_e32 v242, 16, v144
	v_add_u32_e32 v217, v95, v112
	v_add_u32_e32 v224, s71, v114
	v_add_u32_e32 v231, s3, v118
	v_add_u32_e32 v226, s83, v102
	v_add_u32_e32 v234, s67, v120
	v_add_u32_e32 v223, s67, v113
	v_add_u32_e32 v211, v93, v45
	v_add_u32_e32 v218, v96, v112
	v_add_u32_e32 v229, s3, v117
	v_xor_b32_e32 v243, 32, v144
	v_add_u32_e32 v207, v92, v45
	v_add_u32_e32 v230, s69, v117
	v_add_u32_e32 v236, s69, v121
	v_add_u32_e32 v239, 0x12600, v97
	v_add_u32_e32 v208, v94, v108
	v_add_u32_e32 v213, s67, v109
	v_add_u32_e32 v227, s67, v115
	v_add_u32_e32 v235, s3, v121
	v_add_u32_e32 v212, v91, v45
	v_add_u32_e32 v21, 64, v241
	v_cmp_lt_i32_e32 vcc, v242, v21
	s_nop 1
	v_cndmask_b32_e32 v20, v144, v242, vcc
	v_lshlrev_b32_e32 v221, 2, v20
	v_add_u32_e32 v209, v95, v108
	v_add_u32_e32 v215, v92, v111
	v_add_u32_e32 v228, s67, v116
	v_add_u32_e32 v214, s71, v110
	v_cmp_lt_i32_e32 vcc, v243, v21
	s_nop 1
	v_cndmask_b32_e32 v22, v144, v243, vcc
	v_lshlrev_b32_e32 v222, 2, v22
	v_add_u32_e32 v232, s69, v118
	s_waitcnt vmcnt(0)

.Lpk_top:
	v_mov_b32_e32 v0, s48
	ds_write_b32 v0, v129 offset:8
	global_load_dword v1, v129, s[76:77] offset:2560 sc1
	s_waitcnt vmcnt(0)
	v_readfirstlane_b32 s4, v1
	s_nop 1
	s_cmpk_gt_u32 s4, 0x1ff
	s_cbranch_scc1 .Lpk_claim
	s_lshr_b32 s12, s4, 2
	s_and_b32 s12, s12, 7
	s_lshl_b32 s12, s12, 4
	s_lshr_b32 s13, s4, 5
	s_add_i32 s12, s12, s13
	s_lshl_b32 s12, s12, 8
	v_mov_b32_e32 v0, s12
	global_load_dword v1, v0, s[72:73] sc1
	s_waitcnt vmcnt(0)
	v_readfirstlane_b32 s12, v1
	s_nop 1
	s_cmp_gt_u32 s12, 15
	s_cbranch_scc1 .Lpk_claim
	s_mov_b32 s15, 0
.Lpk_q:
	s_add_i32 s12, s2, s15
	s_and_b32 s12, s12, 7
	s_lshl_b32 s13, s12, 7
	v_mov_b32_e32 v0, s13
	global_load_dword v1, v0, s[76:77] offset:3072 sc1
	s_waitcnt vmcnt(0)
	v_readfirstlane_b32 s13, v1
	s_nop 1
	s_cmp_gt_u32 s13, 63
	s_cbranch_scc1 .Lpk_next
	s_lshr_b32 s13, s13, 2
	s_lshl_b32 s14, s12, 4
	s_add_i32 s13, s13, s14
	s_lshl_b32 s13, s13, 8
	v_mov_b32_e32 v2, s13
	global_load_dword v1, v2, s[56:57] sc1
	s_waitcnt vmcnt(0)
	v_readfirstlane_b32 s13, v1
	s_nop 1
	s_cmp_gt_u32 s13, 3
	s_cbranch_scc0 .Lpk_next
	v_mov_b32_e32 v1, 1
	global_atomic_add v1, v0, v1, s[76:77] offset:3072 sc0
	s_waitcnt vmcnt(0)
	v_readfirstlane_b32 s13, v1
	s_nop 1
	s_cmp_gt_u32 s13, 63
	s_cbranch_scc0 .Lpk_got
.Lpk_next:
	s_add_i32 s15, s15, 1
	s_cmp_lt_u32 s15, 8
	s_cbranch_scc1 .Lpk_q
	s_branch .Lpk_sleep
.Lpk_got:
	s_lshr_b32 s14, s13, 2
	s_lshl_b32 s16, s12, 4
	s_add_i32 s14, s14, s16
	s_lshl_b32 s14, s14, 8
	v_mov_b32_e32 v2, s14

.LBB0_1235:
	s_nop 7
	v_or_b32_e32 v130, s54, v143
	v_lshl_or_b32 v131, v142, 11, s55
	s_lshl_b32 s10, s20, 9
	v_readlane_b32 s18, v255, 6
	v_or_b32_e32 v132, v131, v130
	s_or_b32 s10, s21, s10
	v_readlane_b32 s19, v255, 7
	v_add_u32_e32 v128, s10, v132
	v_readlane_b32 s14, v255, 2
	v_readlane_b32 s15, v255, 3
	s_mov_b64 s[14:15], s[18:19]
	global_load_dwordx4 v[156:159], v128, s[24:25]
	s_nop 2
	global_load_dwordx4 v[160:163], v128, s[14:15]
	v_or_b32_e32 v134, 0x100, v128
	global_load_dwordx4 v[168:171], v128, s[14:15] offset:256
	global_load_dwordx4 v[164:167], v134, s[24:25]
	v_add_u32_e32 v250, 0x8000, v128
	v_mov_b32_e32 v251, v129
	global_load_dwordx4 v[172:175], v250, s[24:25]
	global_load_dwordx4 v[176:179], v250, s[14:15]
	global_load_dwordx4 v[184:187], v250, s[14:15] offset:256
	v_lshl_add_u64 v[216:217], s[22:23], 0, v[250:251]
	v_lshl_add_u64 v[212:213], s[22:23], 0, v[128:129]
	v_lshl_add_u64 v[218:219], v[216:217], 0, s[8:9]
	v_lshl_add_u64 v[214:215], v[212:213], 0, s[8:9]
	v_readlane_b32 s16, v255, 4
	v_readlane_b32 s17, v255, 5
	v_readlane_b32 s12, v255, 0
	v_readlane_b32 s13, v255, 1
	s_mov_b64 s[12:13], s[16:17]
	s_waitcnt vmcnt(6)
	v_cvt_f32_f16_e32 v138, v157
	v_cvt_f32_f16_sdwa v139, v157 dst_sel:DWORD dst_unused:UNUSED_PAD src0_sel:WORD_1
	v_cvt_f32_f16_e32 v144, v156
	v_cvt_f32_f16_sdwa v145, v156 dst_sel:DWORD dst_unused:UNUSED_PAD src0_sel:WORD_1
	v_cvt_f32_f16_e32 v148, v159
	v_cvt_f32_f16_sdwa v149, v159 dst_sel:DWORD dst_unused:UNUSED_PAD src0_sel:WORD_1
	v_cvt_f32_f16_e32 v150, v158
	v_cvt_f32_f16_sdwa v151, v158 dst_sel:DWORD dst_unused:UNUSED_PAD src0_sel:WORD_1
	s_waitcnt vmcnt(5)
	v_cvt_f32_f16_e32 v154, v161
	v_cvt_f32_f16_sdwa v155, v161 dst_sel:DWORD dst_unused:UNUSED_PAD src0_sel:WORD_1
	v_cvt_f32_f16_e32 v244, v160
	v_cvt_f32_f16_sdwa v245, v160 dst_sel:DWORD dst_unused:UNUSED_PAD src0_sel:WORD_1
	v_cvt_f32_f16_e32 v246, v163
	v_cvt_f32_f16_e32 v248, v162
	v_cvt_f32_f16_sdwa v249, v162 dst_sel:DWORD dst_unused:UNUSED_PAD src0_sel:WORD_1
	v_cvt_f32_f16_sdwa v247, v163 dst_sel:DWORD dst_unused:UNUSED_PAD src0_sel:WORD_1
	v_pk_fma_f32 v[124:125], v[124:125], v[244:245], v[144:145]
	v_pk_fma_f32 v[126:127], v[126:127], v[154:155], v[138:139]
	v_pk_fma_f32 v[120:121], v[120:121], v[248:249], v[150:151]
	v_pk_fma_f32 v[122:123], v[122:123], v[246:247], v[148:149]
	s_waitcnt vmcnt(3)
	v_cvt_f32_f16_e32 v132, v164
	v_cvt_f32_f16_sdwa v133, v164 dst_sel:DWORD dst_unused:UNUSED_PAD src0_sel:WORD_1
	v_cvt_f32_f16_e32 v144, v167
	v_cvt_f32_f16_sdwa v145, v167 dst_sel:DWORD dst_unused:UNUSED_PAD src0_sel:WORD_1
	v_cvt_f32_f16_e32 v244, v166
	v_cvt_f32_f16_sdwa v245, v166 dst_sel:DWORD dst_unused:UNUSED_PAD src0_sel:WORD_1
	v_cvt_f32_f16_e32 v154, v168
	v_cvt_f32_f16_sdwa v155, v168 dst_sel:DWORD dst_unused:UNUSED_PAD src0_sel:WORD_1
	v_cvt_f32_f16_e32 v150, v171
	v_cvt_f32_f16_e32 v248, v170
	v_cvt_f32_f16_sdwa v249, v170 dst_sel:DWORD dst_unused:UNUSED_PAD src0_sel:WORD_1
	v_cvt_f32_f16_sdwa v151, v171 dst_sel:DWORD dst_unused:UNUSED_PAD src0_sel:WORD_1
	v_add_u32_e32 v148, 0x8100, v128
	v_pk_fma_f32 v[116:117], v[116:117], v[154:155], v[132:133]
	v_pk_fma_f32 v[112:113], v[112:113], v[248:249], v[244:245]
	v_pk_fma_f32 v[114:115], v[114:115], v[150:151], v[144:145]
	global_load_dwordx4 v[180:183], v148, s[24:25]
	s_waitcnt vmcnt(3)
	v_cvt_f32_f16_e32 v132, v175
	v_cvt_f32_f16_sdwa v133, v175 dst_sel:DWORD dst_unused:UNUSED_PAD src0_sel:WORD_1
	s_waitcnt vmcnt(2)
	v_cvt_f32_f16_e32 v244, v179
	v_cvt_f32_f16_sdwa v245, v179 dst_sel:DWORD dst_unused:UNUSED_PAD src0_sel:WORD_1
	v_add_u32_e32 v144, 0x10000, v128
	v_pk_fma_f32 v[106:107], v[106:107], v[244:245], v[132:133]
	global_load_dwordx4 v[188:191], v144, s[24:25]
	global_load_dwordx4 v[192:195], v144, s[14:15]
	v_add_u32_e32 v244, 0x10100, v128
	global_load_dwordx4 v[200:203], v144, s[14:15] offset:256
	global_load_dwordx4 v[196:199], v244, s[24:25]
	v_cvt_f32_f16_e32 v252, v165
	v_cvt_f32_f16_sdwa v253, v165 dst_sel:DWORD dst_unused:UNUSED_PAD src0_sel:WORD_1
	v_cvt_f32_f16_e32 v138, v169
	v_cvt_f32_f16_sdwa v139, v169 dst_sel:DWORD dst_unused:UNUSED_PAD src0_sel:WORD_1
	v_cvt_f32_f16_e32 v246, v173
	v_pk_fma_f32 v[118:119], v[118:119], v[138:139], v[252:253]
	v_cvt_f32_f16_sdwa v247, v173 dst_sel:DWORD dst_unused:UNUSED_PAD src0_sel:WORD_1
	v_cvt_f32_f16_e32 v134, v172
	v_cvt_f32_f16_sdwa v135, v172 dst_sel:DWORD dst_unused:UNUSED_PAD src0_sel:WORD_1
	v_cvt_f32_f16_e32 v154, v174
	v_cvt_f32_f16_sdwa v155, v174 dst_sel:DWORD dst_unused:UNUSED_PAD src0_sel:WORD_1
	v_cvt_f32_f16_e32 v138, v177
	v_cvt_f32_f16_sdwa v139, v177 dst_sel:DWORD dst_unused:UNUSED_PAD src0_sel:WORD_1
	v_cvt_f32_f16_e32 v252, v176
	v_cvt_f32_f16_sdwa v253, v176 dst_sel:DWORD dst_unused:UNUSED_PAD src0_sel:WORD_1
	v_cvt_f32_f16_e32 v248, v178
	v_cvt_f32_f16_sdwa v249, v178 dst_sel:DWORD dst_unused:UNUSED_PAD src0_sel:WORD_1
	v_pk_fma_f32 v[108:109], v[108:109], v[252:253], v[134:135]
	v_pk_fma_f32 v[110:111], v[110:111], v[138:139], v[246:247]
	v_pk_fma_f32 v[104:105], v[104:105], v[248:249], v[154:155]
	s_waitcnt vmcnt(5)
	v_cvt_f32_f16_e32 v246, v185
	v_cvt_f32_f16_sdwa v247, v185 dst_sel:DWORD dst_unused:UNUSED_PAD src0_sel:WORD_1
	v_cvt_f32_f16_e32 v154, v184
	v_cvt_f32_f16_sdwa v155, v184 dst_sel:DWORD dst_unused:UNUSED_PAD src0_sel:WORD_1
	v_cvt_f32_f16_e32 v132, v186
	v_cvt_f32_f16_sdwa v133, v186 dst_sel:DWORD dst_unused:UNUSED_PAD src0_sel:WORD_1
	v_cvt_f32_f16_e32 v248, v187
	v_cvt_f32_f16_sdwa v249, v187 dst_sel:DWORD dst_unused:UNUSED_PAD src0_sel:WORD_1
	v_mov_b32_e32 v145, v129
	v_cvt_pk_f16_f32 v123, v122, v123
	v_lshl_add_u64 v[220:221], s[22:23], 0, v[144:145]
	v_cvt_pk_f16_f32 v122, v120, v121
	v_cvt_pk_f16_f32 v115, v114, v115
	v_cvt_pk_f16_f32 v121, v126, v127
	v_cvt_pk_f16_f32 v120, v124, v125
	v_cvt_pk_f16_f32 v114, v112, v113
	v_cvt_pk_f16_f32 v107, v106, v107
	v_cvt_pk_f16_f32 v113, v118, v119
	v_cvt_pk_f16_f32 v112, v116, v117
	v_cvt_pk_f16_f32 v106, v104, v105
	v_cvt_pk_f16_f32 v105, v110, v111
	v_cvt_pk_f16_f32 v104, v108, v109
	v_lshl_add_u64 v[222:223], v[220:221], 0, s[8:9]
	s_waitcnt vmcnt(4)
	v_cvt_f32_f16_e32 v150, v181
	v_cvt_f32_f16_sdwa v151, v181 dst_sel:DWORD dst_unused:UNUSED_PAD src0_sel:WORD_1
	v_cvt_f32_f16_e32 v134, v180
	v_cvt_f32_f16_sdwa v135, v180 dst_sel:DWORD dst_unused:UNUSED_PAD src0_sel:WORD_1
	v_cvt_f32_f16_e32 v138, v182
	v_cvt_f32_f16_sdwa v139, v182 dst_sel:DWORD dst_unused:UNUSED_PAD src0_sel:WORD_1
	v_pk_fma_f32 v[100:101], v[100:101], v[154:155], v[134:135]
	v_pk_fma_f32 v[102:103], v[102:103], v[246:247], v[150:151]
	v_pk_fma_f32 v[96:97], v[96:97], v[132:133], v[138:139]
	s_waitcnt vmcnt(3)
	v_cvt_f32_f16_e32 v250, v188
	v_cvt_f32_f16_sdwa v251, v188 dst_sel:DWORD dst_unused:UNUSED_PAD src0_sel:WORD_1
	v_cvt_f32_f16_e32 v154, v190
	v_cvt_f32_f16_sdwa v155, v190 dst_sel:DWORD dst_unused:UNUSED_PAD src0_sel:WORD_1
	s_waitcnt vmcnt(2)
	v_cvt_f32_f16_e32 v246, v192
	v_cvt_f32_f16_sdwa v247, v192 dst_sel:DWORD dst_unused:UNUSED_PAD src0_sel:WORD_1
	v_cvt_f32_f16_e32 v138, v194
	v_cvt_f32_f16_sdwa v139, v194 dst_sel:DWORD dst_unused:UNUSED_PAD src0_sel:WORD_1
	v_cvt_f32_f16_e32 v252, v183
	v_cvt_f32_f16_sdwa v253, v183 dst_sel:DWORD dst_unused:UNUSED_PAD src0_sel:WORD_1
	v_pk_fma_f32 v[92:93], v[92:93], v[246:247], v[250:251]
	v_pk_fma_f32 v[88:89], v[88:89], v[138:139], v[154:155]
	s_waitcnt vmcnt(0)
	v_cvt_f32_f16_e32 v250, v199
	v_cvt_f32_f16_sdwa v251, v199 dst_sel:DWORD dst_unused:UNUSED_PAD src0_sel:WORD_1
	v_cvt_f32_f16_e32 v154, v203
	v_cvt_f32_f16_sdwa v155, v203 dst_sel:DWORD dst_unused:UNUSED_PAD src0_sel:WORD_1
	v_pk_fma_f32 v[98:99], v[98:99], v[248:249], v[252:253]
	v_cvt_f32_f16_e32 v134, v191
	v_cvt_f32_f16_sdwa v135, v191 dst_sel:DWORD dst_unused:UNUSED_PAD src0_sel:WORD_1
	v_cvt_f32_f16_e32 v132, v195
	v_cvt_f32_f16_sdwa v133, v195 dst_sel:DWORD dst_unused:UNUSED_PAD src0_sel:WORD_1
	v_add_u32_e32 v248, 0x18000, v128
	v_pk_fma_f32 v[82:83], v[82:83], v[154:155], v[250:251]
	v_or_b32_e32 v154, s10, v130
	v_pk_fma_f32 v[90:91], v[90:91], v[132:133], v[134:135]
	global_load_dwordx4 v[204:207], v248, s[24:25]
	global_load_dwordx4 v[208:211], v248, s[14:15]
	v_add_u32_e32 v134, 0x18100, v128
	v_add_u32_e32 v250, v131, v154
	global_load_dwordx4 v[156:159], v134, s[24:25]
	global_load_dwordx4 v[160:163], v248, s[14:15] offset:256
	v_add_u32_e32 v128, 0x40000, v250
	v_add_u32_e32 v135, 0x40100, v250
	global_load_dwordx4 v[164:167], v128, s[24:25]
	global_load_dwordx4 v[168:171], v128, s[14:15]
	v_lshl_add_u64 v[228:229], s[22:23], 0, v[128:129]
	global_load_dwordx4 v[172:175], v135, s[24:25]
	global_load_dwordx4 v[176:179], v128, s[14:15] offset:256
	v_add_u32_e32 v128, 0x48000, v250
	v_add_u32_e32 v134, 0x48100, v250
	global_load_dwordx4 v[180:183], v128, s[24:25]
	global_load_dwordx4 v[184:187], v128, s[14:15]
	v_cvt_f32_f16_e32 v148, v189
	v_cvt_f32_f16_sdwa v149, v189 dst_sel:DWORD dst_unused:UNUSED_PAD src0_sel:WORD_1
	v_cvt_f32_f16_e32 v150, v193
	v_cvt_f32_f16_sdwa v151, v193 dst_sel:DWORD dst_unused:UNUSED_PAD src0_sel:WORD_1
	v_lshl_add_u64 v[232:233], s[22:23], 0, v[128:129]
	global_load_dwordx4 v[188:191], v134, s[24:25]
	global_load_dwordx4 v[192:195], v128, s[14:15] offset:256
	v_add_u32_e32 v128, 0x50000, v250
	v_pk_fma_f32 v[94:95], v[94:95], v[150:151], v[148:149]
	v_cvt_f32_f16_e32 v252, v197
	v_cvt_f32_f16_sdwa v253, v197 dst_sel:DWORD dst_unused:UNUSED_PAD src0_sel:WORD_1
	v_cvt_f32_f16_e32 v246, v196
	v_cvt_f32_f16_sdwa v247, v196 dst_sel:DWORD dst_unused:UNUSED_PAD src0_sel:WORD_1
	v_cvt_f32_f16_e32 v148, v198
	v_cvt_f32_f16_sdwa v149, v198 dst_sel:DWORD dst_unused:UNUSED_PAD src0_sel:WORD_1
	v_cvt_f32_f16_e32 v150, v201
	v_cvt_f32_f16_sdwa v151, v201 dst_sel:DWORD dst_unused:UNUSED_PAD src0_sel:WORD_1
	v_cvt_f32_f16_e32 v138, v200
	v_cvt_f32_f16_sdwa v139, v200 dst_sel:DWORD dst_unused:UNUSED_PAD src0_sel:WORD_1
	v_cvt_f32_f16_e32 v132, v202
	v_cvt_f32_f16_sdwa v133, v202 dst_sel:DWORD dst_unused:UNUSED_PAD src0_sel:WORD_1
	global_load_dwordx4 v[196:199], v128, s[24:25]
	global_load_dwordx4 v[200:203], v128, s[14:15]
	v_pk_fma_f32 v[84:85], v[84:85], v[138:139], v[246:247]
	v_pk_fma_f32 v[86:87], v[86:87], v[150:151], v[252:253]
	v_pk_fma_f32 v[80:81], v[80:81], v[132:133], v[148:149]
	v_mov_b32_e32 v249, v129
	v_lshl_add_u64 v[236:237], s[22:23], 0, v[128:129]
	v_lshl_add_u64 v[224:225], s[22:23], 0, v[248:249]
	v_cvt_pk_f16_f32 v99, v98, v99
	v_cvt_pk_f16_f32 v98, v96, v97
	v_cvt_pk_f16_f32 v91, v90, v91
	v_cvt_pk_f16_f32 v97, v102, v103
	v_cvt_pk_f16_f32 v96, v100, v101
	v_cvt_pk_f16_f32 v90, v88, v89
	v_cvt_pk_f16_f32 v83, v82, v83
	v_cvt_pk_f16_f32 v89, v94, v95
	v_cvt_pk_f16_f32 v88, v92, v93
	v_cvt_pk_f16_f32 v82, v80, v81
	v_cvt_pk_f16_f32 v81, v86, v87
	v_cvt_pk_f16_f32 v80, v84, v85
	v_lshl_add_u64 v[226:227], v[224:225], 0, s[8:9]
	v_lshl_add_u64 v[230:231], v[228:229], 0, s[8:9]
	v_lshl_add_u64 v[234:235], v[232:233], 0, s[8:9]
	v_lshl_add_u64 v[238:239], v[236:237], 0, s[8:9]
	s_waitcnt vmcnt(13)
	v_cvt_f32_f16_e32 v244, v205
	v_cvt_f32_f16_sdwa v245, v205 dst_sel:DWORD dst_unused:UNUSED_PAD src0_sel:WORD_1
	v_cvt_f32_f16_e32 v144, v204
	v_cvt_f32_f16_sdwa v145, v204 dst_sel:DWORD dst_unused:UNUSED_PAD src0_sel:WORD_1
	v_cvt_f32_f16_e32 v138, v207
	v_cvt_f32_f16_sdwa v139, v207 dst_sel:DWORD dst_unused:UNUSED_PAD src0_sel:WORD_1
	v_cvt_f32_f16_e32 v246, v206
	v_cvt_f32_f16_sdwa v247, v206 dst_sel:DWORD dst_unused:UNUSED_PAD src0_sel:WORD_1
	s_waitcnt vmcnt(12)
	v_cvt_f32_f16_e32 v150, v209
	v_cvt_f32_f16_sdwa v151, v209 dst_sel:DWORD dst_unused:UNUSED_PAD src0_sel:WORD_1
	v_cvt_f32_f16_e32 v252, v208
	v_cvt_f32_f16_sdwa v253, v208 dst_sel:DWORD dst_unused:UNUSED_PAD src0_sel:WORD_1
	v_cvt_f32_f16_e32 v132, v211
	v_cvt_f32_f16_e32 v148, v210
	v_cvt_f32_f16_sdwa v149, v210 dst_sel:DWORD dst_unused:UNUSED_PAD src0_sel:WORD_1
	v_cvt_f32_f16_sdwa v133, v211 dst_sel:DWORD dst_unused:UNUSED_PAD src0_sel:WORD_1
	v_pk_fma_f32 v[76:77], v[76:77], v[252:253], v[144:145]
	v_pk_fma_f32 v[78:79], v[78:79], v[150:151], v[244:245]
	v_pk_fma_f32 v[72:73], v[72:73], v[148:149], v[246:247]
	v_pk_fma_f32 v[74:75], v[74:75], v[132:133], v[138:139]
	s_waitcnt vmcnt(11)
	v_cvt_f32_f16_e32 v144, v157
	v_cvt_f32_f16_sdwa v145, v157 dst_sel:DWORD dst_unused:UNUSED_PAD src0_sel:WORD_1
	v_cvt_f32_f16_e32 v252, v156
	v_cvt_f32_f16_sdwa v253, v156 dst_sel:DWORD dst_unused:UNUSED_PAD src0_sel:WORD_1
	v_cvt_f32_f16_e32 v244, v158
	v_cvt_f32_f16_sdwa v245, v158 dst_sel:DWORD dst_unused:UNUSED_PAD src0_sel:WORD_1
	s_waitcnt vmcnt(10)
	v_cvt_f32_f16_e32 v148, v161
	v_cvt_f32_f16_sdwa v149, v161 dst_sel:DWORD dst_unused:UNUSED_PAD src0_sel:WORD_1
	v_cvt_f32_f16_e32 v246, v160
	v_cvt_f32_f16_sdwa v247, v160 dst_sel:DWORD dst_unused:UNUSED_PAD src0_sel:WORD_1
	v_cvt_f32_f16_e32 v138, v162
	v_cvt_f32_f16_sdwa v139, v162 dst_sel:DWORD dst_unused:UNUSED_PAD src0_sel:WORD_1
	v_pk_fma_f32 v[68:69], v[68:69], v[246:247], v[252:253]
	v_pk_fma_f32 v[70:71], v[70:71], v[148:149], v[144:145]
	v_pk_fma_f32 v[64:65], v[64:65], v[138:139], v[244:245]
	v_cvt_f32_f16_e32 v150, v159
	v_cvt_f32_f16_sdwa v151, v159 dst_sel:DWORD dst_unused:UNUSED_PAD src0_sel:WORD_1
	v_cvt_f32_f16_e32 v132, v163
	v_cvt_f32_f16_sdwa v133, v163 dst_sel:DWORD dst_unused:UNUSED_PAD src0_sel:WORD_1
	s_waitcnt vmcnt(9)
	v_cvt_f32_f16_e32 v248, v165
	v_cvt_f32_f16_sdwa v249, v165 dst_sel:DWORD dst_unused:UNUSED_PAD src0_sel:WORD_1
	v_cvt_f32_f16_e32 v130, v164
	v_cvt_f32_f16_sdwa v131, v164 dst_sel:DWORD dst_unused:UNUSED_PAD src0_sel:WORD_1
	v_cvt_f32_f16_e32 v246, v166
	v_cvt_f32_f16_sdwa v247, v166 dst_sel:DWORD dst_unused:UNUSED_PAD src0_sel:WORD_1
	s_waitcnt vmcnt(8)
	v_cvt_f32_f16_e32 v252, v169
	v_cvt_f32_f16_sdwa v253, v169 dst_sel:DWORD dst_unused:UNUSED_PAD src0_sel:WORD_1
	v_cvt_f32_f16_e32 v144, v168
	v_cvt_f32_f16_sdwa v145, v168 dst_sel:DWORD dst_unused:UNUSED_PAD src0_sel:WORD_1
	v_cvt_f32_f16_e32 v138, v170
	v_cvt_f32_f16_sdwa v139, v170 dst_sel:DWORD dst_unused:UNUSED_PAD src0_sel:WORD_1
	v_pk_fma_f32 v[66:67], v[66:67], v[132:133], v[150:151]
	v_pk_fma_f32 v[60:61], v[60:61], v[144:145], v[130:131]
	v_pk_fma_f32 v[62:63], v[62:63], v[252:253], v[248:249]
	v_pk_fma_f32 v[56:57], v[56:57], v[138:139], v[246:247]
	v_cvt_f32_f16_e32 v154, v167
	v_cvt_f32_f16_sdwa v155, v167 dst_sel:DWORD dst_unused:UNUSED_PAD src0_sel:WORD_1
	v_cvt_f32_f16_e32 v148, v171
	v_cvt_f32_f16_sdwa v149, v171 dst_sel:DWORD dst_unused:UNUSED_PAD src0_sel:WORD_1
	s_waitcnt vmcnt(7)
	v_cvt_f32_f16_e32 v244, v173
	v_cvt_f32_f16_sdwa v245, v173 dst_sel:DWORD dst_unused:UNUSED_PAD src0_sel:WORD_1
	v_cvt_f32_f16_e32 v132, v172
	v_cvt_f32_f16_sdwa v133, v172 dst_sel:DWORD dst_unused:UNUSED_PAD src0_sel:WORD_1
	v_cvt_f32_f16_e32 v130, v174
	v_cvt_f32_f16_sdwa v131, v174 dst_sel:DWORD dst_unused:UNUSED_PAD src0_sel:WORD_1
	s_waitcnt vmcnt(6)
	v_cvt_f32_f16_e32 v144, v177
	v_cvt_f32_f16_sdwa v145, v177 dst_sel:DWORD dst_unused:UNUSED_PAD src0_sel:WORD_1
	v_cvt_f32_f16_e32 v248, v176
	v_cvt_f32_f16_sdwa v249, v176 dst_sel:DWORD dst_unused:UNUSED_PAD src0_sel:WORD_1
	v_cvt_f32_f16_e32 v138, v178
	v_cvt_f32_f16_sdwa v139, v178 dst_sel:DWORD dst_unused:UNUSED_PAD src0_sel:WORD_1
	v_pk_fma_f32 v[58:59], v[58:59], v[148:149], v[154:155]
	v_pk_fma_f32 v[52:53], v[52:53], v[248:249], v[132:133]
	v_pk_fma_f32 v[54:55], v[54:55], v[144:145], v[244:245]
	v_pk_fma_f32 v[48:49], v[48:49], v[138:139], v[130:131]
	v_cvt_f32_f16_e32 v150, v175
	v_cvt_f32_f16_sdwa v151, v175 dst_sel:DWORD dst_unused:UNUSED_PAD src0_sel:WORD_1
	v_cvt_f32_f16_e32 v252, v179
	v_cvt_f32_f16_sdwa v253, v179 dst_sel:DWORD dst_unused:UNUSED_PAD src0_sel:WORD_1
	s_waitcnt vmcnt(5)
	v_cvt_f32_f16_e32 v246, v181
	v_cvt_f32_f16_sdwa v247, v181 dst_sel:DWORD dst_unused:UNUSED_PAD src0_sel:WORD_1
	v_cvt_f32_f16_e32 v148, v180
	v_cvt_f32_f16_sdwa v149, v180 dst_sel:DWORD dst_unused:UNUSED_PAD src0_sel:WORD_1
	v_cvt_f32_f16_e32 v132, v182
	v_cvt_f32_f16_sdwa v133, v182 dst_sel:DWORD dst_unused:UNUSED_PAD src0_sel:WORD_1
	s_waitcnt vmcnt(4)
	v_cvt_f32_f16_e32 v248, v185
	v_cvt_f32_f16_sdwa v249, v185 dst_sel:DWORD dst_unused:UNUSED_PAD src0_sel:WORD_1
	v_cvt_f32_f16_e32 v144, v184
	v_cvt_f32_f16_sdwa v145, v184 dst_sel:DWORD dst_unused:UNUSED_PAD src0_sel:WORD_1
	v_cvt_f32_f16_e32 v130, v186
	v_cvt_f32_f16_sdwa v131, v186 dst_sel:DWORD dst_unused:UNUSED_PAD src0_sel:WORD_1
	v_pk_fma_f32 v[50:51], v[50:51], v[252:253], v[150:151]
	v_pk_fma_f32 v[44:45], v[44:45], v[144:145], v[148:149]
	v_pk_fma_f32 v[46:47], v[46:47], v[248:249], v[246:247]
	v_pk_fma_f32 v[40:41], v[40:41], v[130:131], v[132:133]
	s_waitcnt vmcnt(3)
	v_cvt_f32_f16_e32 v150, v188
	v_cvt_f32_f16_sdwa v151, v188 dst_sel:DWORD dst_unused:UNUSED_PAD src0_sel:WORD_1
	v_cvt_f32_f16_e32 v144, v190
	v_cvt_f32_f16_sdwa v145, v190 dst_sel:DWORD dst_unused:UNUSED_PAD src0_sel:WORD_1
	s_waitcnt vmcnt(2)
	v_cvt_f32_f16_e32 v246, v192
	v_cvt_f32_f16_sdwa v247, v192 dst_sel:DWORD dst_unused:UNUSED_PAD src0_sel:WORD_1
	v_cvt_f32_f16_e32 v130, v194
	v_cvt_f32_f16_sdwa v131, v194 dst_sel:DWORD dst_unused:UNUSED_PAD src0_sel:WORD_1
	v_add_u32_e32 v132, 0x50100, v250
	v_pk_fma_f32 v[36:37], v[36:37], v[246:247], v[150:151]
	v_pk_fma_f32 v[32:33], v[32:33], v[130:131], v[144:145]
	global_load_dwordx4 v[204:207], v132, s[24:25]
	global_load_dwordx4 v[208:211], v128, s[14:15] offset:256
	s_waitcnt vmcnt(3)
	v_cvt_f32_f16_e32 v150, v198
	v_cvt_f32_f16_sdwa v151, v198 dst_sel:DWORD dst_unused:UNUSED_PAD src0_sel:WORD_1
	s_waitcnt vmcnt(2)
	v_cvt_f32_f16_e32 v130, v202
	v_cvt_f32_f16_sdwa v131, v202 dst_sel:DWORD dst_unused:UNUSED_PAD src0_sel:WORD_1
	v_add_u32_e32 v128, 0x58000, v250
	v_pk_fma_f32 v[24:25], v[24:25], v[130:131], v[150:151]
	global_load_dwordx4 v[156:159], v128, s[24:25]
	global_load_dwordx4 v[160:163], v128, s[14:15]
	v_add_u32_e32 v150, 0x58100, v250
	global_load_dwordx4 v[168:171], v128, s[14:15] offset:256
	global_load_dwordx4 v[164:167], v150, s[24:25]
	v_cvt_f32_f16_e32 v154, v183
	v_cvt_f32_f16_sdwa v155, v183 dst_sel:DWORD dst_unused:UNUSED_PAD src0_sel:WORD_1
	v_cvt_f32_f16_e32 v244, v187
	v_cvt_f32_f16_sdwa v245, v187 dst_sel:DWORD dst_unused:UNUSED_PAD src0_sel:WORD_1
	v_cvt_f32_f16_e32 v138, v189
	v_cvt_f32_f16_sdwa v139, v189 dst_sel:DWORD dst_unused:UNUSED_PAD src0_sel:WORD_1
	v_cvt_f32_f16_e32 v148, v193
	v_cvt_f32_f16_sdwa v149, v193 dst_sel:DWORD dst_unused:UNUSED_PAD src0_sel:WORD_1
	v_pk_fma_f32 v[42:43], v[42:43], v[244:245], v[154:155]
	v_cvt_f32_f16_e32 v252, v191
	v_cvt_f32_f16_sdwa v253, v191 dst_sel:DWORD dst_unused:UNUSED_PAD src0_sel:WORD_1
	v_cvt_f32_f16_e32 v248, v195
	v_cvt_f32_f16_sdwa v249, v195 dst_sel:DWORD dst_unused:UNUSED_PAD src0_sel:WORD_1
	v_cvt_f32_f16_e32 v154, v197
	v_cvt_f32_f16_sdwa v155, v197 dst_sel:DWORD dst_unused:UNUSED_PAD src0_sel:WORD_1
	v_cvt_f32_f16_e32 v246, v201
	v_cvt_f32_f16_sdwa v247, v201 dst_sel:DWORD dst_unused:UNUSED_PAD src0_sel:WORD_1
	v_pk_fma_f32 v[38:39], v[38:39], v[148:149], v[138:139]
	v_cvt_f32_f16_e32 v244, v196
	v_cvt_f32_f16_sdwa v245, v196 dst_sel:DWORD dst_unused:UNUSED_PAD src0_sel:WORD_1
	v_cvt_f32_f16_e32 v138, v200
	v_cvt_f32_f16_sdwa v139, v200 dst_sel:DWORD dst_unused:UNUSED_PAD src0_sel:WORD_1
	v_pk_fma_f32 v[34:35], v[34:35], v[248:249], v[252:253]
	v_pk_fma_f32 v[30:31], v[30:31], v[246:247], v[154:155]
	v_cvt_f32_f16_e32 v134, v199
	v_cvt_f32_f16_sdwa v135, v199 dst_sel:DWORD dst_unused:UNUSED_PAD src0_sel:WORD_1
	v_cvt_f32_f16_e32 v148, v203
	v_cvt_f32_f16_sdwa v149, v203 dst_sel:DWORD dst_unused:UNUSED_PAD src0_sel:WORD_1
	v_pk_fma_f32 v[28:29], v[28:29], v[138:139], v[244:245]
	v_pk_fma_f32 v[26:27], v[26:27], v[148:149], v[134:135]
	v_cvt_pk_f16_f32 v75, v74, v75
	v_cvt_pk_f16_f32 v74, v72, v73
	v_cvt_pk_f16_f32 v67, v66, v67
	v_cvt_pk_f16_f32 v73, v78, v79
	v_cvt_pk_f16_f32 v72, v76, v77
	v_cvt_pk_f16_f32 v66, v64, v65
	v_cvt_pk_f16_f32 v59, v58, v59
	v_cvt_pk_f16_f32 v65, v70, v71
	v_cvt_pk_f16_f32 v64, v68, v69
	v_cvt_pk_f16_f32 v58, v56, v57
	v_cvt_pk_f16_f32 v51, v50, v51
	v_lshl_add_u64 v[240:241], s[22:23], 0, v[128:129]
	global_store_dwordx4 v[212:213], v[120:123], off sc1
	s_nop 1
	v_cvt_pk_f16_f32 v57, v62, v63
	v_cvt_pk_f16_f32 v56, v60, v61
	v_cvt_pk_f16_f32 v50, v48, v49
	v_cvt_pk_f16_f32 v43, v42, v43
	global_store_dwordx4 v[214:215], v[112:115], off sc1
	s_nop 1
	v_cvt_pk_f16_f32 v49, v54, v55
	v_cvt_pk_f16_f32 v48, v52, v53
	v_cvt_pk_f16_f32 v42, v40, v41
	v_cvt_pk_f16_f32 v35, v34, v35
	global_store_dwordx4 v[216:217], v[104:107], off sc1
	s_nop 1
	v_cvt_pk_f16_f32 v41, v46, v47
	v_cvt_pk_f16_f32 v40, v44, v45
	v_cvt_pk_f16_f32 v34, v32, v33
	v_cvt_pk_f16_f32 v27, v26, v27
	global_store_dwordx4 v[218:219], v[96:99], off sc1
	s_nop 1
	v_cvt_pk_f16_f32 v33, v38, v39
	v_cvt_pk_f16_f32 v32, v36, v37
	v_cvt_pk_f16_f32 v26, v24, v25
	global_store_dwordx4 v[220:221], v[88:91], off sc1
	s_nop 1
	v_cvt_pk_f16_f32 v25, v30, v31
	v_cvt_pk_f16_f32 v24, v28, v29
	global_store_dwordx4 v[222:223], v[80:83], off sc1
	s_nop 1
	global_store_dwordx4 v[224:225], v[72:75], off sc1
	s_nop 1
	global_store_dwordx4 v[226:227], v[64:67], off sc1
	s_nop 1
	v_lshl_add_u64 v[242:243], v[240:241], 0, s[8:9]
	global_store_dwordx4 v[228:229], v[56:59], off sc1
	s_nop 1
	global_store_dwordx4 v[230:231], v[48:51], off sc1
	s_nop 1
	global_store_dwordx4 v[232:233], v[40:43], off sc1
	s_nop 1
	global_store_dwordx4 v[234:235], v[32:35], off sc1
	s_nop 1
	global_store_dwordx4 v[236:237], v[24:27], off sc1
	s_nop 1
	s_waitcnt vmcnt(18)
	v_cvt_f32_f16_e32 v248, v204
	v_cvt_f32_f16_sdwa v249, v204 dst_sel:DWORD dst_unused:UNUSED_PAD src0_sel:WORD_1
	v_cvt_f32_f16_e32 v144, v205
	s_waitcnt vmcnt(17)
	v_cvt_f32_f16_e32 v154, v208
	v_cvt_f32_f16_sdwa v155, v208 dst_sel:DWORD dst_unused:UNUSED_PAD src0_sel:WORD_1
	v_cvt_f32_f16_sdwa v145, v205 dst_sel:DWORD dst_unused:UNUSED_PAD src0_sel:WORD_1
	v_cvt_f32_f16_e32 v244, v209
	v_cvt_f32_f16_sdwa v245, v209 dst_sel:DWORD dst_unused:UNUSED_PAD src0_sel:WORD_1
	v_pk_fma_f32 v[20:21], v[20:21], v[154:155], v[248:249]
	v_cvt_f32_f16_e32 v252, v207
	v_cvt_f32_f16_sdwa v253, v207 dst_sel:DWORD dst_unused:UNUSED_PAD src0_sel:WORD_1
	v_cvt_f32_f16_e32 v138, v206
	v_cvt_f32_f16_sdwa v139, v206 dst_sel:DWORD dst_unused:UNUSED_PAD src0_sel:WORD_1
	v_cvt_f32_f16_e32 v246, v211
	v_cvt_f32_f16_e32 v130, v210
	v_cvt_f32_f16_sdwa v131, v210 dst_sel:DWORD dst_unused:UNUSED_PAD src0_sel:WORD_1
	v_cvt_f32_f16_sdwa v247, v211 dst_sel:DWORD dst_unused:UNUSED_PAD src0_sel:WORD_1
	s_waitcnt vmcnt(16)
	v_cvt_f32_f16_e32 v134, v157
	v_cvt_f32_f16_sdwa v135, v157 dst_sel:DWORD dst_unused:UNUSED_PAD src0_sel:WORD_1
	s_waitcnt vmcnt(15)
	v_cvt_f32_f16_e32 v248, v161
	v_cvt_f32_f16_sdwa v249, v161 dst_sel:DWORD dst_unused:UNUSED_PAD src0_sel:WORD_1
	v_pk_fma_f32 v[22:23], v[22:23], v[244:245], v[144:145]
	v_cvt_f32_f16_e32 v148, v156
	v_cvt_f32_f16_sdwa v149, v156 dst_sel:DWORD dst_unused:UNUSED_PAD src0_sel:WORD_1
	v_cvt_f32_f16_e32 v144, v160
	v_cvt_f32_f16_sdwa v145, v160 dst_sel:DWORD dst_unused:UNUSED_PAD src0_sel:WORD_1
	v_pk_fma_f32 v[16:17], v[16:17], v[130:131], v[138:139]
	v_pk_fma_f32 v[18:19], v[18:19], v[246:247], v[252:253]
	v_cvt_f32_f16_e32 v132, v159
	v_cvt_f32_f16_sdwa v133, v159 dst_sel:DWORD dst_unused:UNUSED_PAD src0_sel:WORD_1
	v_cvt_f32_f16_e32 v244, v163
	v_cvt_f32_f16_sdwa v245, v163 dst_sel:DWORD dst_unused:UNUSED_PAD src0_sel:WORD_1
	v_pk_fma_f32 v[14:15], v[14:15], v[248:249], v[134:135]
	v_cvt_f32_f16_e32 v154, v158
	v_cvt_f32_f16_sdwa v155, v158 dst_sel:DWORD dst_unused:UNUSED_PAD src0_sel:WORD_1
	v_cvt_f32_f16_e32 v130, v162
	v_cvt_f32_f16_sdwa v131, v162 dst_sel:DWORD dst_unused:UNUSED_PAD src0_sel:WORD_1
	s_waitcnt vmcnt(13)
	v_cvt_f32_f16_e32 v252, v167
	v_cvt_f32_f16_sdwa v253, v167 dst_sel:DWORD dst_unused:UNUSED_PAD src0_sel:WORD_1
	v_cvt_f32_f16_e32 v134, v171
	v_cvt_f32_f16_sdwa v135, v171 dst_sel:DWORD dst_unused:UNUSED_PAD src0_sel:WORD_1
	v_pk_fma_f32 v[12:13], v[12:13], v[144:145], v[148:149]
	v_cvt_f32_f16_e32 v250, v166
	v_cvt_f32_f16_sdwa v251, v166 dst_sel:DWORD dst_unused:UNUSED_PAD src0_sel:WORD_1
	v_cvt_f32_f16_e32 v248, v170
	v_cvt_f32_f16_sdwa v249, v170 dst_sel:DWORD dst_unused:UNUSED_PAD src0_sel:WORD_1
	v_cvt_f32_f16_e32 v138, v165
	v_cvt_f32_f16_sdwa v139, v165 dst_sel:DWORD dst_unused:UNUSED_PAD src0_sel:WORD_1
	v_cvt_f32_f16_e32 v246, v164
	v_cvt_f32_f16_sdwa v247, v164 dst_sel:DWORD dst_unused:UNUSED_PAD src0_sel:WORD_1
	v_cvt_f32_f16_e32 v144, v169
	v_cvt_f32_f16_sdwa v145, v169 dst_sel:DWORD dst_unused:UNUSED_PAD src0_sel:WORD_1
	v_cvt_f32_f16_e32 v148, v168
	v_cvt_f32_f16_sdwa v149, v168 dst_sel:DWORD dst_unused:UNUSED_PAD src0_sel:WORD_1
	v_pk_fma_f32 v[10:11], v[10:11], v[244:245], v[132:133]
	v_pk_fma_f32 v[8:9], v[8:9], v[130:131], v[154:155]
	v_pk_fma_f32 v[2:3], v[2:3], v[134:135], v[252:253]
	v_pk_fma_f32 v[0:1], v[0:1], v[248:249], v[250:251]
	v_pk_fma_f32 v[4:5], v[4:5], v[148:149], v[246:247]
	v_pk_fma_f32 v[6:7], v[6:7], v[144:145], v[138:139]
	v_cvt_pk_f16_f32 v19, v18, v19
	v_cvt_pk_f16_f32 v18, v16, v17
	v_cvt_pk_f16_f32 v11, v10, v11
	v_cvt_pk_f16_f32 v17, v22, v23
	v_cvt_pk_f16_f32 v16, v20, v21
	v_cvt_pk_f16_f32 v10, v8, v9
	v_cvt_pk_f16_f32 v3, v2, v3
	v_cvt_pk_f16_f32 v9, v14, v15
	v_cvt_pk_f16_f32 v8, v12, v13
	v_cvt_pk_f16_f32 v2, v0, v1
	v_cvt_pk_f16_f32 v1, v6, v7
	v_cvt_pk_f16_f32 v0, v4, v5
	global_store_dwordx4 v[238:239], v[16:19], off sc1
	s_nop 1
	global_store_dwordx4 v[240:241], v[8:11], off sc1
	s_nop 1
	global_store_dwordx4 v[242:243], v[0:3], off sc1
	s_nop 1
	s_waitcnt vmcnt(0)
	s_barrier
	v_mbcnt_lo_u32_b32 v0, -1, 0
	v_mbcnt_hi_u32_b32 v0, -1, v0
	s_nop 0
	v_or_b32_e32 v0, s97, v0
	v_cmp_eq_u32_e32 vcc, 0, v0
	s_and_saveexec_b64 s[10:11], vcc
	s_cbranch_execz .LBB0_1199
	s_mov_b64 s[14:15], exec
	v_mbcnt_lo_u32_b32 v0, s14, 0
	v_mbcnt_hi_u32_b32 v0, s15, v0
	v_cmp_eq_u32_e32 vcc, 0, v0
	s_and_saveexec_b64 s[12:13], vcc
	s_cbranch_execz .LBB0_1238
	s_lshl_b32 s4, s4, 6
	s_lshl_b64 s[16:17], s[4:5], 2
	s_add_u32 s16, s56, s16
	s_addc_u32 s17, s57, s17
	s_bcnt1_i32_b64 s4, s[14:15]
	v_mov_b32_e32 v0, s4
	global_atomic_add v129, v0, s[16:17]
